# S5 chunk split between the two scan wave groups retuned 41 -> 40 after the output-step LDS read hoist made output chunks faster
# speedup vs baseline: 1.0099x; 1.0012x over previous
.LBB0_112:
	s_and_b64 s[42:43], s[8:9], s[74:75]
	s_andn2_b64 vcc, exec, s[42:43]
	s_waitcnt lgkmcnt(0)
	s_barrier
	s_cbranch_vccnz .LBB0_131
	s_and_b64 s[42:43], s[76:77], exec
	s_cselect_b32 s39, 0, 40
	s_lshl_b32 s30, s34, 2
	s_and_b32 s30, s30, 0x7c
	s_add_i32 s74, s30, s36
	v_lshl_or_b32 v0, s74, 6, v116
	v_ashrrev_i32_e32 v1, 31, v0
	s_mul_i32 s30, s70, 0x810
	s_mov_b64 s[80:81], -1
	s_and_b64 vcc, exec, s[72:73]
	v_lshl_add_u64 v[96:97], v[0:1], 3, s[24:25]
	v_lshl_or_b32 v98, s74, 8, v116
	v_add_u32_e32 v138, s30, v123
	v_add_u32_e32 v139, s30, v154
	s_cbranch_vccz .LBB0_119
	s_lshl_b32 s78, s74, 4
	s_ashr_i32 s79, s78, 31
	v_lshl_or_b32 v100, s74, 8, v116
	v_lshl_add_u64 v[0:1], s[78:79], 2, v[118:119]
	v_ashrrev_i32_e32 v101, 31, v100
	v_add_u32_e32 v102, s30, v123
	global_load_dwordx2 v[12:13], v[96:97], off
	global_load_dwordx4 v[64:67], v[0:1], off offset:16
	global_load_dwordx4 v[68:71], v[0:1], off
	v_lshl_add_u64 v[0:1], v[100:101], 4, s[62:63]
	v_ashrrev_i32_e32 v103, 31, v102
	global_load_dwordx4 v[72:75], v[0:1], off
	global_load_dwordx4 v[76:79], v[0:1], off offset:1024
	global_load_dwordx4 v[80:83], v[0:1], off offset:2048
	global_load_dwordx4 v[84:87], v[0:1], off offset:3072
	v_lshlrev_b64 v[0:1], 12, v[102:103]
	s_lshl_b64 s[42:43], s[78:79], 1
	v_lshl_add_u64 v[0:1], s[22:23], 0, v[0:1]
	v_lshl_add_u64 v[0:1], v[0:1], 0, s[42:43]
	v_mov_b32_e32 v137, v193
	v_lshl_add_u64 v[0:1], v[0:1], 0, v[136:137]
	global_load_dwordx4 v[8:11], v[0:1], off
	v_add_u32_e32 v137, s30, v154
	v_mov_b32_e32 v140, 0
	v_lshl_add_u64 v[106:107], v[120:121], 0, s[42:43]
	v_mov_b64_e32 v[104:105], v[100:101]
	s_mov_b32 s42, 0
	v_mov_b32_e32 v99, v125
	v_mov_b32_e32 v114, v137
	v_mov_b32_e32 v141, v140
	s_waitcnt vmcnt(7)
	v_xor_b32_e32 v108, 0x80000000, v13
	v_mov_b32_e32 v110, v12
	v_mov_b32_e32 v111, v12
	v_mov_b32_e32 v109, v13
	v_mov_b32_e32 v112, v13
	v_mov_b32_e32 v113, v108
	s_waitcnt vmcnt(0)
	v_lshlrev_b32_e32 v6, 16, v11
	v_and_b32_e32 v7, 0xffff0000, v11
	v_lshlrev_b32_e32 v2, 16, v9
	v_and_b32_e32 v3, 0xffff0000, v9
	v_lshlrev_b32_e32 v4, 16, v10
	v_and_b32_e32 v5, 0xffff0000, v10
	v_lshlrev_b32_e32 v0, 16, v8
	v_and_b32_e32 v1, 0xffff0000, v8
	v_mov_b64_e32 v[94:95], v[6:7]
	v_mov_b64_e32 v[90:91], v[2:3]
	v_mov_b64_e32 v[92:93], v[4:5]
	v_mov_b64_e32 v[88:89], v[0:1]
	s_branch .LBB0_116

.LBB0_121:
	v_or_b32_e32 v8, 64, v100
	v_lshlrev_b64 v[4:5], 4, v[104:105]
	v_ashrrev_i32_e32 v9, 31, v8
	v_lshl_add_u64 v[6:7], s[64:65], 0, v[4:5]
	v_lshlrev_b64 v[10:11], 4, v[8:9]
	global_load_dwordx2 v[138:139], v[96:97], off
	v_lshl_add_u64 v[8:9], s[64:65], 0, v[10:11]
	global_load_dwordx4 v[64:67], v[6:7], off
	global_load_dwordx4 v[68:71], v[8:9], off
	v_or_b32_e32 v6, 0x80, v100
	v_ashrrev_i32_e32 v7, 31, v6
	v_or_b32_e32 v8, 0xc0, v100
	v_lshlrev_b64 v[16:17], 2, v[0:1]
	s_and_b64 s[42:43], s[76:77], exec
	v_lshlrev_b64 v[12:13], 4, v[6:7]
	v_ashrrev_i32_e32 v9, 31, v8
	v_lshl_add_u64 v[18:19], s[26:27], 0, v[16:17]
	v_lshl_add_u64 v[6:7], s[64:65], 0, v[12:13]
	v_lshlrev_b64 v[14:15], 4, v[8:9]
	v_lshlrev_b32_e32 v3, 2, v122
	v_readfirstlane_b32 s42, v18
	v_readfirstlane_b32 s43, v19
	s_cselect_b32 s30, 40, 0x41
	v_lshl_add_u64 v[8:9], s[64:65], 0, v[14:15]
	global_load_dwordx4 v[72:75], v[6:7], off
	global_load_dwordx4 v[76:79], v[8:9], off
	s_nop 0
	global_load_dwordx4 v[80:83], v3, s[42:43] offset:16
	global_load_dwordx4 v[84:87], v3, s[42:43]
	s_lshl_b32 s42, s39, 5
	v_add_u32_e32 v6, s42, v102
	v_ashrrev_i32_e32 v7, 31, v6
	v_lshlrev_b64 v[6:7], 12, v[6:7]
	v_lshlrev_b64 v[0:1], 1, v[0:1]
	v_lshl_add_u64 v[6:7], s[22:23], 0, v[6:7]
	v_lshlrev_b32_e32 v192, 1, v122
	v_lshl_add_u64 v[6:7], v[6:7], 0, v[0:1]
	v_lshl_add_u64 v[6:7], v[6:7], 0, v[192:193]
	global_load_dwordx4 v[6:9], v[6:7], off
	v_lshl_add_u64 v[16:17], v[126:127], 0, v[16:17]
	v_lshl_add_u64 v[4:5], s[62:63], 0, v[4:5]
	global_load_dwordx4 v[88:91], v[16:17], off
	v_lshl_add_u64 v[10:11], s[62:63], 0, v[10:11]
	global_load_dwordx4 v[92:95], v[4:5], off
	global_load_dwordx4 v[96:99], v[10:11], off
	v_lshl_add_u64 v[4:5], s[62:63], 0, v[12:13]
	v_lshl_add_u64 v[10:11], s[62:63], 0, v[14:15]
	global_load_dwordx4 v[100:103], v[4:5], off
	global_load_dwordx4 v[104:107], v[10:11], off
	v_add_u32_e32 v164, v155, v2
	v_lshl_add_u64 v[2:3], s[22:23], 0, v[0:1]
	v_lshl_add_u64 v[144:145], v[2:3], 0, v[192:193]
	v_lshlrev_b32_e32 v192, 1, v124
	v_lshl_add_u64 v[146:147], v[2:3], 0, v[192:193]
	v_lshl_add_u64 v[142:143], v[128:129], 0, v[0:1]
	s_lshl_b32 s43, s39, 7
	v_lshlrev_b32_e32 v192, 2, v124
	v_add_u32_e32 v165, s43, v161
	v_add_u32_e32 v166, s43, v125
	s_sub_i32 s43, 32, s42
	v_lshl_add_u64 v[148:149], v[18:19], 0, v[192:193]
	global_load_dwordx4 v[182:185], v[148:149], off
	s_waitcnt vmcnt(13)
	v_xor_b32_e32 v151, 0x80000000, v139
	v_mov_b32_e32 v152, v138
	v_mov_b32_e32 v153, v138
	v_mov_b32_e32 v150, v139
	v_mov_b32_e32 v138, v151
	s_waitcnt vmcnt(6)
	v_lshlrev_b32_e32 v2, 16, v9
	v_and_b32_e32 v3, 0xffff0000, v9
	v_lshlrev_b32_e32 v4, 16, v6
	v_and_b32_e32 v5, 0xffff0000, v6
	v_lshlrev_b32_e32 v6, 16, v7
	v_and_b32_e32 v7, 0xffff0000, v7
	v_lshlrev_b32_e32 v0, 16, v8
	v_and_b32_e32 v1, 0xffff0000, v8
	v_mov_b64_e32 v[114:115], v[2:3]
	v_mov_b64_e32 v[110:111], v[6:7]
	v_mov_b64_e32 v[112:113], v[0:1]
	v_mov_b64_e32 v[108:109], v[4:5]
	s_waitcnt vmcnt(0)
	s_branch .LBB0_123
